# mixer-A unit epilogue: subLN row reductions via DPP instead of 4 serialized ds_swizzle round trips per row
# speedup vs baseline: 1.0110x; 1.0099x over previous
.LBB0_405:
	s_or_b64 exec, exec, s[4:5]
	s_waitcnt lgkmcnt(0)
	v_lshlrev_b32_e32 v129, 2, v134
	global_load_dword v132, v129, s[0:1]
	global_load_dword v131, v129, s[0:1] offset:128
	global_load_dword v130, v129, s[0:1] offset:256
	s_nop 0
	global_load_dword v129, v129, s[0:1] offset:384
	v_ashrrev_i32_e32 v135, 3, v128
	v_and_b32_e32 v139, -4, v135
	v_mov_b32_e32 v133, v200
	v_lshl_add_u32 v143, v134, 1, s48
	v_lshl_add_u32 v134, v139, 2, s59
	ds_read_b96 v[136:138], v134
	ds_read_b96 v[140:142], v134 offset:128
	v_sub_f32_e32 v133, 1.0, v133
	s_add_i32 s6, s6, 1
	s_cmp_eq_u32 s6, 4
	s_waitcnt lgkmcnt(0)
	v_mul_f32_e32 v16, v16, v140
	v_mul_f32_e32 v0, v0, v140
	v_fma_f32 v16, v80, v136, -v16
	v_fma_f32 v0, v64, v136, -v0
	v_mul_f32_e32 v64, v16, v16
	v_mul_f32_e32 v32, v32, v140
	v_fmac_f32_e32 v64, v0, v0
	v_fma_f32 v80, v96, v136, -v32
	v_mul_f32_e32 v32, v48, v140
	v_fmac_f32_e32 v64, v80, v80
	v_fma_f32 v48, v112, v136, -v32
	v_fmac_f32_e32 v64, v48, v48
	s_nop 1
	s_waitcnt lgkmcnt(0)
	v_add_f32_dpp v32, v64, v64 quad_perm:[1,0,3,2] row_mask:0xf bank_mask:0xf
	s_nop 1
	v_add_f32_dpp v32, v32, v32 quad_perm:[2,3,0,1] row_mask:0xf bank_mask:0xf
	s_nop 1
	v_add_f32_dpp v32, v32, v32 row_half_mirror row_mask:0xf bank_mask:0xf
	s_nop 1
	v_add_f32_dpp v32, v32, v32 row_mirror row_mask:0xf bank_mask:0xf
	ds_swizzle_b32 v64, v32 offset:swizzle(SWAP,16)
	s_waitcnt lgkmcnt(0)
	v_add_f32_e32 v32, v32, v64
	v_fmamk_f32 v32, v32, 0x3c000000, v204
	v_rsq_f32_e32 v32, v32
	s_nop 0
	v_mul_f32_e32 v64, v133, v32
	v_mul_f32_e32 v0, v0, v64
	v_mul_f32_e32 v16, v16, v64
	v_lshl_add_u32 v32, v139, 8, v143
	v_mul_f32_e32 v80, v80, v64
	v_mul_f32_e32 v48, v48, v64
	s_waitcnt vmcnt(3)
	v_mul_f32_e32 v0, v132, v0
	s_waitcnt vmcnt(2)
	v_mul_f32_e32 v16, v131, v16
	v_cvt_pk_bf16_f32 v0, v0, s0
	s_waitcnt vmcnt(1)
	v_mul_f32_e32 v80, v130, v80
	ds_write_b16 v32, v0
	v_cvt_pk_bf16_f32 v0, v16, s0
	s_waitcnt vmcnt(0)
	v_mul_f32_e32 v48, v129, v48
	ds_write_b16 v32, v0 offset:64
	v_cvt_pk_bf16_f32 v0, v80, s0
	ds_write_b16 v32, v0 offset:128
	v_cvt_pk_bf16_f32 v0, v48, s0
	ds_write_b16 v32, v0 offset:192
	v_mul_f32_e32 v0, v1, v141
	v_mul_f32_e32 v1, v17, v141
	v_fma_f32 v1, v81, v137, -v1
	v_fma_f32 v0, v65, v137, -v0
	v_mul_f32_e32 v16, v1, v1
	v_mul_f32_e32 v17, v33, v141
	v_fmac_f32_e32 v16, v0, v0
	v_fma_f32 v17, v97, v137, -v17
	v_mul_f32_e32 v33, v49, v141
	v_fmac_f32_e32 v16, v17, v17
	v_fma_f32 v33, v113, v137, -v33
	v_fmac_f32_e32 v16, v33, v33
	s_nop 1
	s_waitcnt lgkmcnt(0)
	v_add_f32_dpp v16, v16, v16 quad_perm:[1,0,3,2] row_mask:0xf bank_mask:0xf
	s_nop 1
	v_add_f32_dpp v16, v16, v16 quad_perm:[2,3,0,1] row_mask:0xf bank_mask:0xf
	s_nop 1
	v_add_f32_dpp v16, v16, v16 row_half_mirror row_mask:0xf bank_mask:0xf
	s_nop 1
	v_add_f32_dpp v16, v16, v16 row_mirror row_mask:0xf bank_mask:0xf
	ds_swizzle_b32 v48, v16 offset:swizzle(SWAP,16)
	s_waitcnt lgkmcnt(0)
	v_add_f32_e32 v16, v16, v48
	v_fmamk_f32 v16, v16, 0x3c000000, v204
	v_rsq_f32_e32 v16, v16
	s_nop 0
	v_mul_f32_e32 v16, v133, v16
	v_mul_f32_e32 v0, v0, v16
	v_mul_f32_e32 v0, v132, v0
	v_mul_f32_e32 v1, v1, v16
	v_mul_f32_e32 v1, v131, v1
	v_mul_f32_e32 v17, v17, v16
	v_cvt_pk_bf16_f32 v0, v0, s0
	v_mul_f32_e32 v17, v130, v17
	v_mul_f32_e32 v16, v33, v16
	ds_write_b16 v32, v0 offset:256
	v_cvt_pk_bf16_f32 v0, v1, s0
	v_mul_f32_e32 v16, v129, v16
	ds_write_b16 v32, v0 offset:320
	v_cvt_pk_bf16_f32 v0, v17, s0
	ds_write_b16 v32, v0 offset:384
	v_cvt_pk_bf16_f32 v0, v16, s0
	v_mul_f32_e32 v1, v18, v142
	ds_write_b16 v32, v0 offset:448
	v_mul_f32_e32 v0, v2, v142
	v_fma_f32 v1, v82, v138, -v1
	v_fma_f32 v0, v66, v138, -v0
	v_mul_f32_e32 v2, v1, v1
	v_mul_f32_e32 v16, v34, v142
	v_fmac_f32_e32 v2, v0, v0
	v_fma_f32 v16, v98, v138, -v16
	v_mul_f32_e32 v17, v50, v142
	v_fmac_f32_e32 v2, v16, v16
	v_fma_f32 v17, v114, v138, -v17
	v_fmac_f32_e32 v2, v17, v17
	s_nop 1
	s_waitcnt lgkmcnt(0)
	v_add_f32_dpp v2, v2, v2 quad_perm:[1,0,3,2] row_mask:0xf bank_mask:0xf
	s_nop 1
	v_add_f32_dpp v2, v2, v2 quad_perm:[2,3,0,1] row_mask:0xf bank_mask:0xf
	s_nop 1
	v_add_f32_dpp v2, v2, v2 row_half_mirror row_mask:0xf bank_mask:0xf
	s_nop 1
	v_add_f32_dpp v2, v2, v2 row_mirror row_mask:0xf bank_mask:0xf
	ds_swizzle_b32 v18, v2 offset:swizzle(SWAP,16)
	s_waitcnt lgkmcnt(0)
	v_add_f32_e32 v2, v2, v18
	v_fmamk_f32 v2, v2, 0x3c000000, v204
	v_rsq_f32_e32 v2, v2
	s_nop 0
	v_mul_f32_e32 v2, v133, v2
	v_mul_f32_e32 v0, v0, v2
	v_mul_f32_e32 v0, v132, v0
	v_mul_f32_e32 v1, v1, v2
	v_mul_f32_e32 v1, v131, v1
	v_mul_f32_e32 v16, v16, v2
	v_cvt_pk_bf16_f32 v0, v0, s0
	v_mul_f32_e32 v16, v130, v16
	v_mul_f32_e32 v2, v17, v2
	ds_write_b16 v32, v0 offset:512
	v_cvt_pk_bf16_f32 v0, v1, s0
	v_mul_f32_e32 v2, v129, v2
	ds_write_b16 v32, v0 offset:576
	v_cvt_pk_bf16_f32 v0, v16, s0
	ds_write_b16 v32, v0 offset:640
	v_cvt_pk_bf16_f32 v0, v2, s0
	v_or_b32_e32 v2, 3, v135
	ds_write_b16 v32, v0 offset:704
	v_lshl_add_u32 v0, v2, 2, s59
	ds_read2_b32 v[0:1], v0 offset1:32
	v_lshl_add_u32 v2, v2, 8, v143
	s_waitcnt lgkmcnt(0)
	v_mul_f32_e32 v16, v19, v1
	v_mul_f32_e32 v3, v3, v1
	v_fma_f32 v16, v83, v0, -v16
	v_fma_f32 v3, v67, v0, -v3
	v_mul_f32_e32 v17, v16, v16
	v_mul_f32_e32 v18, v35, v1
	v_fmac_f32_e32 v17, v3, v3
	v_fma_f32 v18, v99, v0, -v18
	v_mul_f32_e32 v1, v51, v1
	v_fmac_f32_e32 v17, v18, v18
	v_fma_f32 v0, v115, v0, -v1
	v_fmac_f32_e32 v17, v0, v0
	s_nop 1
	s_waitcnt lgkmcnt(0)
	v_add_f32_dpp v1, v17, v17 quad_perm:[1,0,3,2] row_mask:0xf bank_mask:0xf
	s_nop 1
	v_add_f32_dpp v1, v1, v1 quad_perm:[2,3,0,1] row_mask:0xf bank_mask:0xf
	s_nop 1
	v_add_f32_dpp v1, v1, v1 row_half_mirror row_mask:0xf bank_mask:0xf
	s_nop 1
	v_add_f32_dpp v1, v1, v1 row_mirror row_mask:0xf bank_mask:0xf
	ds_swizzle_b32 v17, v1 offset:swizzle(SWAP,16)
	s_waitcnt lgkmcnt(0)
	v_add_f32_e32 v1, v1, v17
	v_fmamk_f32 v1, v1, 0x3c000000, v204
	v_rsq_f32_e32 v1, v1
	s_nop 0
	v_mul_f32_e32 v1, v133, v1
	v_mul_f32_e32 v3, v3, v1
	v_mul_f32_e32 v3, v132, v3
	v_mul_f32_e32 v16, v16, v1
	v_mul_f32_e32 v16, v131, v16
	v_mul_f32_e32 v17, v18, v1
	v_mul_f32_e32 v0, v0, v1
	v_cvt_pk_bf16_f32 v1, v3, s0
	v_mul_f32_e32 v17, v130, v17
	v_mul_f32_e32 v0, v129, v0
	ds_write_b16 v2, v1
	v_cvt_pk_bf16_f32 v1, v16, s0
	ds_write_b16 v2, v1 offset:64
	v_cvt_pk_bf16_f32 v1, v17, s0
	v_cvt_pk_bf16_f32 v0, v0, s0
	ds_write_b16 v2, v1 offset:128
	ds_write_b16 v2, v0 offset:192
	ds_read_b128 v[0:3], v134 offset:32
	ds_read_b128 v[16:19], v134 offset:160
	s_waitcnt lgkmcnt(0)
	v_mul_f32_e32 v20, v20, v16
	v_mul_f32_e32 v4, v4, v16
	v_fma_f32 v20, v84, v0, -v20
	v_fma_f32 v4, v68, v0, -v4
	v_mul_f32_e32 v33, v20, v20
	v_mul_f32_e32 v34, v36, v16
	v_fmac_f32_e32 v33, v4, v4
	v_fma_f32 v34, v100, v0, -v34
	v_mul_f32_e32 v16, v52, v16
	v_fmac_f32_e32 v33, v34, v34
	v_fma_f32 v0, v116, v0, -v16
	v_fmac_f32_e32 v33, v0, v0
	s_nop 1
	s_waitcnt lgkmcnt(0)
	v_add_f32_dpp v16, v33, v33 quad_perm:[1,0,3,2] row_mask:0xf bank_mask:0xf
	s_nop 1
	v_add_f32_dpp v16, v16, v16 quad_perm:[2,3,0,1] row_mask:0xf bank_mask:0xf
	s_nop 1
	v_add_f32_dpp v16, v16, v16 row_half_mirror row_mask:0xf bank_mask:0xf
	s_nop 1
	v_add_f32_dpp v16, v16, v16 row_mirror row_mask:0xf bank_mask:0xf
	ds_swizzle_b32 v33, v16 offset:swizzle(SWAP,16)
	s_waitcnt lgkmcnt(0)
	v_add_f32_e32 v16, v16, v33
	v_fmamk_f32 v16, v16, 0x3c000000, v204
	v_rsq_f32_e32 v16, v16
	s_nop 0
	v_mul_f32_e32 v16, v133, v16
	v_mul_f32_e32 v4, v4, v16
	v_mul_f32_e32 v4, v132, v4
	v_mul_f32_e32 v20, v20, v16
	v_mul_f32_e32 v20, v131, v20
	v_mul_f32_e32 v33, v34, v16
	v_cvt_pk_bf16_f32 v4, v4, s0
	v_mul_f32_e32 v33, v130, v33
	v_mul_f32_e32 v0, v0, v16
	ds_write_b16 v32, v4 offset:2048
	v_cvt_pk_bf16_f32 v4, v20, s0
	v_mul_f32_e32 v0, v129, v0
	ds_write_b16 v32, v4 offset:2112
	v_cvt_pk_bf16_f32 v4, v33, s0
	ds_write_b16 v32, v4 offset:2176
	v_cvt_pk_bf16_f32 v0, v0, s0
	v_mul_f32_e32 v4, v21, v17
	ds_write_b16 v32, v0 offset:2240
	v_mul_f32_e32 v0, v5, v17
	v_fma_f32 v4, v85, v1, -v4
	v_fma_f32 v0, v69, v1, -v0
	v_mul_f32_e32 v5, v4, v4
	v_mul_f32_e32 v16, v37, v17
	v_fmac_f32_e32 v5, v0, v0
	v_fma_f32 v16, v101, v1, -v16
	v_mul_f32_e32 v17, v53, v17
	v_fmac_f32_e32 v5, v16, v16
	v_fma_f32 v1, v117, v1, -v17
	v_fmac_f32_e32 v5, v1, v1
	s_nop 1
	s_waitcnt lgkmcnt(0)
	v_add_f32_dpp v5, v5, v5 quad_perm:[1,0,3,2] row_mask:0xf bank_mask:0xf
	s_nop 1
	v_add_f32_dpp v5, v5, v5 quad_perm:[2,3,0,1] row_mask:0xf bank_mask:0xf
	s_nop 1
	v_add_f32_dpp v5, v5, v5 row_half_mirror row_mask:0xf bank_mask:0xf
	s_nop 1
	v_add_f32_dpp v5, v5, v5 row_mirror row_mask:0xf bank_mask:0xf
	ds_swizzle_b32 v17, v5 offset:swizzle(SWAP,16)
	s_waitcnt lgkmcnt(0)
	v_add_f32_e32 v5, v5, v17
	v_fmamk_f32 v5, v5, 0x3c000000, v204
	v_rsq_f32_e32 v5, v5
	s_nop 0
	v_mul_f32_e32 v5, v133, v5
	v_mul_f32_e32 v0, v0, v5
	v_mul_f32_e32 v0, v132, v0
	v_mul_f32_e32 v4, v4, v5
	v_mul_f32_e32 v4, v131, v4
	v_mul_f32_e32 v16, v16, v5
	v_cvt_pk_bf16_f32 v0, v0, s0
	v_mul_f32_e32 v16, v130, v16
	v_mul_f32_e32 v1, v1, v5
	ds_write_b16 v32, v0 offset:2304
	v_cvt_pk_bf16_f32 v0, v4, s0
	v_mul_f32_e32 v1, v129, v1
	ds_write_b16 v32, v0 offset:2368
	v_cvt_pk_bf16_f32 v0, v16, s0
	ds_write_b16 v32, v0 offset:2432
	v_cvt_pk_bf16_f32 v0, v1, s0
	v_mul_f32_e32 v1, v22, v18
	ds_write_b16 v32, v0 offset:2496
	v_mul_f32_e32 v0, v6, v18
	v_fma_f32 v1, v86, v2, -v1
	v_fma_f32 v0, v70, v2, -v0
	v_mul_f32_e32 v4, v1, v1
	v_mul_f32_e32 v5, v38, v18
	v_fmac_f32_e32 v4, v0, v0
	v_fma_f32 v5, v102, v2, -v5
	v_mul_f32_e32 v6, v54, v18
	v_fmac_f32_e32 v4, v5, v5
	v_fma_f32 v2, v118, v2, -v6
	v_fmac_f32_e32 v4, v2, v2
	s_nop 1
	s_waitcnt lgkmcnt(0)
	v_add_f32_dpp v4, v4, v4 quad_perm:[1,0,3,2] row_mask:0xf bank_mask:0xf
	s_nop 1
	v_add_f32_dpp v4, v4, v4 quad_perm:[2,3,0,1] row_mask:0xf bank_mask:0xf
	s_nop 1
	v_add_f32_dpp v4, v4, v4 row_half_mirror row_mask:0xf bank_mask:0xf
	s_nop 1
	v_add_f32_dpp v4, v4, v4 row_mirror row_mask:0xf bank_mask:0xf
	ds_swizzle_b32 v6, v4 offset:swizzle(SWAP,16)
	s_waitcnt lgkmcnt(0)
	v_add_f32_e32 v4, v4, v6
	v_fmamk_f32 v4, v4, 0x3c000000, v204
	v_rsq_f32_e32 v4, v4
	s_nop 0
	v_mul_f32_e32 v4, v133, v4
	v_mul_f32_e32 v0, v0, v4
	v_mul_f32_e32 v0, v132, v0
	v_mul_f32_e32 v1, v1, v4
	v_mul_f32_e32 v1, v131, v1
	v_mul_f32_e32 v5, v5, v4
	v_cvt_pk_bf16_f32 v0, v0, s0
	v_mul_f32_e32 v5, v130, v5
	v_mul_f32_e32 v2, v2, v4
	ds_write_b16 v32, v0 offset:2560
	v_cvt_pk_bf16_f32 v0, v1, s0
	v_mul_f32_e32 v2, v129, v2
	ds_write_b16 v32, v0 offset:2624
	v_cvt_pk_bf16_f32 v0, v5, s0
	ds_write_b16 v32, v0 offset:2688
	v_cvt_pk_bf16_f32 v0, v2, s0
	v_mul_f32_e32 v1, v23, v19
	ds_write_b16 v32, v0 offset:2752
	v_mul_f32_e32 v0, v7, v19
	v_fma_f32 v1, v87, v3, -v1
	v_fma_f32 v0, v71, v3, -v0
	v_mul_f32_e32 v2, v1, v1
	v_mul_f32_e32 v4, v39, v19
	v_fmac_f32_e32 v2, v0, v0
	v_fma_f32 v4, v103, v3, -v4
	v_mul_f32_e32 v5, v55, v19
	v_fmac_f32_e32 v2, v4, v4
	v_fma_f32 v3, v119, v3, -v5
	v_fmac_f32_e32 v2, v3, v3
	s_nop 1
	s_waitcnt lgkmcnt(0)
	v_add_f32_dpp v2, v2, v2 quad_perm:[1,0,3,2] row_mask:0xf bank_mask:0xf
	s_nop 1
	v_add_f32_dpp v2, v2, v2 quad_perm:[2,3,0,1] row_mask:0xf bank_mask:0xf
	s_nop 1
	v_add_f32_dpp v2, v2, v2 row_half_mirror row_mask:0xf bank_mask:0xf
	s_nop 1
	v_add_f32_dpp v2, v2, v2 row_mirror row_mask:0xf bank_mask:0xf
	ds_swizzle_b32 v5, v2 offset:swizzle(SWAP,16)
	s_waitcnt lgkmcnt(0)
	v_add_f32_e32 v2, v2, v5
	v_fmamk_f32 v2, v2, 0x3c000000, v204
	v_rsq_f32_e32 v2, v2
	s_nop 0
	v_mul_f32_e32 v2, v133, v2
	v_mul_f32_e32 v0, v0, v2
	v_mul_f32_e32 v0, v132, v0
	v_mul_f32_e32 v1, v1, v2
	v_mul_f32_e32 v1, v131, v1
	v_mul_f32_e32 v4, v4, v2
	v_cvt_pk_bf16_f32 v0, v0, s0
	v_mul_f32_e32 v4, v130, v4
	v_mul_f32_e32 v2, v3, v2
	ds_write_b16 v32, v0 offset:2816
	v_cvt_pk_bf16_f32 v0, v1, s0
	v_mul_f32_e32 v2, v129, v2
	ds_write_b16 v32, v0 offset:2880
	v_cvt_pk_bf16_f32 v0, v4, s0
	ds_write_b16 v32, v0 offset:2944
	v_cvt_pk_bf16_f32 v0, v2, s0
	ds_write_b16 v32, v0 offset:3008
	ds_read_b128 v[0:3], v134 offset:64
	ds_read_b128 v[4:7], v134 offset:192
	s_waitcnt lgkmcnt(0)
	v_mul_f32_e32 v16, v24, v4
	v_mul_f32_e32 v8, v8, v4
	v_fma_f32 v16, v88, v0, -v16
	v_fma_f32 v8, v72, v0, -v8
	v_mul_f32_e32 v17, v16, v16
	v_mul_f32_e32 v18, v40, v4
	v_fmac_f32_e32 v17, v8, v8
	v_fma_f32 v18, v104, v0, -v18
	v_mul_f32_e32 v4, v56, v4
	v_fmac_f32_e32 v17, v18, v18
	v_fma_f32 v0, v120, v0, -v4
	v_fmac_f32_e32 v17, v0, v0
	s_nop 1
	s_waitcnt lgkmcnt(0)
	v_add_f32_dpp v4, v17, v17 quad_perm:[1,0,3,2] row_mask:0xf bank_mask:0xf
	s_nop 1
	v_add_f32_dpp v4, v4, v4 quad_perm:[2,3,0,1] row_mask:0xf bank_mask:0xf
	s_nop 1
	v_add_f32_dpp v4, v4, v4 row_half_mirror row_mask:0xf bank_mask:0xf
	s_nop 1
	v_add_f32_dpp v4, v4, v4 row_mirror row_mask:0xf bank_mask:0xf
	ds_swizzle_b32 v17, v4 offset:swizzle(SWAP,16)
	s_waitcnt lgkmcnt(0)
	v_add_f32_e32 v4, v4, v17
	v_fmamk_f32 v4, v4, 0x3c000000, v204
	v_rsq_f32_e32 v4, v4
	s_nop 0
	v_mul_f32_e32 v4, v133, v4
	v_mul_f32_e32 v8, v8, v4
	v_mul_f32_e32 v8, v132, v8
	v_mul_f32_e32 v16, v16, v4
	v_mul_f32_e32 v16, v131, v16
	v_mul_f32_e32 v17, v18, v4
	v_mul_f32_e32 v0, v0, v4
	v_cvt_pk_bf16_f32 v4, v8, s0
	v_mul_f32_e32 v17, v130, v17
	ds_write_b16 v32, v4 offset:4096
	v_cvt_pk_bf16_f32 v4, v16, s0
	v_mul_f32_e32 v0, v129, v0
	ds_write_b16 v32, v4 offset:4160
	v_cvt_pk_bf16_f32 v4, v17, s0
	ds_write_b16 v32, v4 offset:4224
	v_cvt_pk_bf16_f32 v0, v0, s0
	v_mul_f32_e32 v4, v25, v5
	ds_write_b16 v32, v0 offset:4288
	v_mul_f32_e32 v0, v9, v5
	v_fma_f32 v4, v89, v1, -v4
	v_fma_f32 v0, v73, v1, -v0
	v_mul_f32_e32 v8, v4, v4
	v_mul_f32_e32 v9, v41, v5
	v_fmac_f32_e32 v8, v0, v0
	v_fma_f32 v9, v105, v1, -v9
	v_mul_f32_e32 v5, v57, v5
	v_fmac_f32_e32 v8, v9, v9
	v_fma_f32 v1, v121, v1, -v5
	v_fmac_f32_e32 v8, v1, v1
	s_nop 1
	s_waitcnt lgkmcnt(0)
	v_add_f32_dpp v5, v8, v8 quad_perm:[1,0,3,2] row_mask:0xf bank_mask:0xf
	s_nop 1
	v_add_f32_dpp v5, v5, v5 quad_perm:[2,3,0,1] row_mask:0xf bank_mask:0xf
	s_nop 1
	v_add_f32_dpp v5, v5, v5 row_half_mirror row_mask:0xf bank_mask:0xf
	s_nop 1
	v_add_f32_dpp v5, v5, v5 row_mirror row_mask:0xf bank_mask:0xf
	ds_swizzle_b32 v8, v5 offset:swizzle(SWAP,16)
	s_waitcnt lgkmcnt(0)
	v_add_f32_e32 v5, v5, v8
	v_fmamk_f32 v5, v5, 0x3c000000, v204
	v_rsq_f32_e32 v5, v5
	s_nop 0
	v_mul_f32_e32 v5, v133, v5
	v_mul_f32_e32 v0, v0, v5
	v_mul_f32_e32 v0, v132, v0
	v_mul_f32_e32 v4, v4, v5
	v_mul_f32_e32 v4, v131, v4
	v_mul_f32_e32 v8, v9, v5
	v_cvt_pk_bf16_f32 v0, v0, s0
	v_mul_f32_e32 v8, v130, v8
	v_mul_f32_e32 v1, v1, v5
	ds_write_b16 v32, v0 offset:4352
	v_cvt_pk_bf16_f32 v0, v4, s0
	v_mul_f32_e32 v1, v129, v1
	ds_write_b16 v32, v0 offset:4416
	v_cvt_pk_bf16_f32 v0, v8, s0
	ds_write_b16 v32, v0 offset:4480
	v_cvt_pk_bf16_f32 v0, v1, s0
	v_mul_f32_e32 v1, v26, v6
	ds_write_b16 v32, v0 offset:4544
	v_mul_f32_e32 v0, v10, v6
	v_fma_f32 v1, v90, v2, -v1
	v_fma_f32 v0, v74, v2, -v0
	v_mul_f32_e32 v4, v1, v1
	v_mul_f32_e32 v5, v42, v6
	v_fmac_f32_e32 v4, v0, v0
	v_fma_f32 v5, v106, v2, -v5
	v_mul_f32_e32 v6, v58, v6
	v_fmac_f32_e32 v4, v5, v5
	v_fma_f32 v2, v122, v2, -v6
	v_fmac_f32_e32 v4, v2, v2
	s_nop 1
	s_waitcnt lgkmcnt(0)
	v_add_f32_dpp v4, v4, v4 quad_perm:[1,0,3,2] row_mask:0xf bank_mask:0xf
	s_nop 1
	v_add_f32_dpp v4, v4, v4 quad_perm:[2,3,0,1] row_mask:0xf bank_mask:0xf
	s_nop 1
	v_add_f32_dpp v4, v4, v4 row_half_mirror row_mask:0xf bank_mask:0xf
	s_nop 1
	v_add_f32_dpp v4, v4, v4 row_mirror row_mask:0xf bank_mask:0xf
	ds_swizzle_b32 v6, v4 offset:swizzle(SWAP,16)
	s_waitcnt lgkmcnt(0)
	v_add_f32_e32 v4, v4, v6
	v_fmamk_f32 v4, v4, 0x3c000000, v204
	v_rsq_f32_e32 v4, v4
	s_nop 0
	v_mul_f32_e32 v4, v133, v4
	v_mul_f32_e32 v0, v0, v4
	v_mul_f32_e32 v0, v132, v0
	v_mul_f32_e32 v1, v1, v4
	v_mul_f32_e32 v1, v131, v1
	v_mul_f32_e32 v5, v5, v4
	v_cvt_pk_bf16_f32 v0, v0, s0
	v_mul_f32_e32 v5, v130, v5
	v_mul_f32_e32 v2, v2, v4
	ds_write_b16 v32, v0 offset:4608
	v_cvt_pk_bf16_f32 v0, v1, s0
	v_mul_f32_e32 v2, v129, v2
	ds_write_b16 v32, v0 offset:4672
	v_cvt_pk_bf16_f32 v0, v5, s0
	ds_write_b16 v32, v0 offset:4736
	v_cvt_pk_bf16_f32 v0, v2, s0
	v_mul_f32_e32 v1, v27, v7
	ds_write_b16 v32, v0 offset:4800
	v_mul_f32_e32 v0, v11, v7
	v_fma_f32 v1, v91, v3, -v1
	v_fma_f32 v0, v75, v3, -v0
	v_mul_f32_e32 v2, v1, v1
	v_mul_f32_e32 v4, v43, v7
	v_fmac_f32_e32 v2, v0, v0
	v_fma_f32 v4, v107, v3, -v4
	v_mul_f32_e32 v5, v59, v7
	v_fmac_f32_e32 v2, v4, v4
	v_fma_f32 v3, v123, v3, -v5
	v_fmac_f32_e32 v2, v3, v3
	s_nop 1
	s_waitcnt lgkmcnt(0)
	v_add_f32_dpp v2, v2, v2 quad_perm:[1,0,3,2] row_mask:0xf bank_mask:0xf
	s_nop 1
	v_add_f32_dpp v2, v2, v2 quad_perm:[2,3,0,1] row_mask:0xf bank_mask:0xf
	s_nop 1
	v_add_f32_dpp v2, v2, v2 row_half_mirror row_mask:0xf bank_mask:0xf
	s_nop 1
	v_add_f32_dpp v2, v2, v2 row_mirror row_mask:0xf bank_mask:0xf
	ds_swizzle_b32 v5, v2 offset:swizzle(SWAP,16)
	s_waitcnt lgkmcnt(0)
	v_add_f32_e32 v2, v2, v5
	v_fmamk_f32 v2, v2, 0x3c000000, v204
	v_rsq_f32_e32 v2, v2
	s_nop 0
	v_mul_f32_e32 v2, v133, v2
	v_mul_f32_e32 v0, v0, v2
	v_mul_f32_e32 v0, v132, v0
	v_mul_f32_e32 v1, v1, v2
	v_mul_f32_e32 v1, v131, v1
	v_mul_f32_e32 v4, v4, v2
	v_cvt_pk_bf16_f32 v0, v0, s0
	v_mul_f32_e32 v4, v130, v4
	v_mul_f32_e32 v2, v3, v2
	ds_write_b16 v32, v0 offset:4864
	v_cvt_pk_bf16_f32 v0, v1, s0
	v_mul_f32_e32 v2, v129, v2
	ds_write_b16 v32, v0 offset:4928
	v_cvt_pk_bf16_f32 v0, v4, s0
	ds_write_b16 v32, v0 offset:4992
	v_cvt_pk_bf16_f32 v0, v2, s0
	ds_write_b16 v32, v0 offset:5056
	ds_read_b128 v[0:3], v134 offset:96
	ds_read_b128 v[4:7], v134 offset:224
	s_waitcnt lgkmcnt(0)
	v_mul_f32_e32 v9, v28, v4
	v_mul_f32_e32 v8, v12, v4
	v_fma_f32 v9, v92, v0, -v9
	v_fma_f32 v8, v76, v0, -v8
	v_mul_f32_e32 v10, v9, v9
	v_mul_f32_e32 v11, v44, v4
	v_fmac_f32_e32 v10, v8, v8
	v_fma_f32 v11, v108, v0, -v11
	v_mul_f32_e32 v4, v60, v4
	v_fmac_f32_e32 v10, v11, v11
	v_fma_f32 v0, v124, v0, -v4
	v_fmac_f32_e32 v10, v0, v0
	s_nop 1
	s_waitcnt lgkmcnt(0)
	v_add_f32_dpp v4, v10, v10 quad_perm:[1,0,3,2] row_mask:0xf bank_mask:0xf
	s_nop 1
	v_add_f32_dpp v4, v4, v4 quad_perm:[2,3,0,1] row_mask:0xf bank_mask:0xf
	s_nop 1
	v_add_f32_dpp v4, v4, v4 row_half_mirror row_mask:0xf bank_mask:0xf
	s_nop 1
	v_add_f32_dpp v4, v4, v4 row_mirror row_mask:0xf bank_mask:0xf
	ds_swizzle_b32 v10, v4 offset:swizzle(SWAP,16)
	s_waitcnt lgkmcnt(0)
	v_add_f32_e32 v4, v4, v10
	v_fmamk_f32 v4, v4, 0x3c000000, v204
	v_rsq_f32_e32 v4, v4
	s_nop 0
	v_mul_f32_e32 v4, v133, v4
	v_mul_f32_e32 v8, v8, v4
	v_mul_f32_e32 v8, v132, v8
	v_mul_f32_e32 v9, v9, v4
	v_mul_f32_e32 v9, v131, v9
	v_mul_f32_e32 v10, v11, v4
	v_mul_f32_e32 v0, v0, v4
	v_cvt_pk_bf16_f32 v4, v8, s0
	v_mul_f32_e32 v10, v130, v10
	ds_write_b16 v32, v4 offset:6144
	v_cvt_pk_bf16_f32 v4, v9, s0
	v_mul_f32_e32 v0, v129, v0
	ds_write_b16 v32, v4 offset:6208
	v_cvt_pk_bf16_f32 v4, v10, s0
	ds_write_b16 v32, v4 offset:6272
	v_cvt_pk_bf16_f32 v0, v0, s0
	v_mul_f32_e32 v4, v29, v5
	ds_write_b16 v32, v0 offset:6336
	v_mul_f32_e32 v0, v13, v5
	v_fma_f32 v4, v93, v1, -v4
	v_fma_f32 v0, v77, v1, -v0
	v_mul_f32_e32 v8, v4, v4
	v_mul_f32_e32 v9, v45, v5
	v_fmac_f32_e32 v8, v0, v0
	v_fma_f32 v9, v109, v1, -v9
	v_mul_f32_e32 v5, v61, v5
	v_fmac_f32_e32 v8, v9, v9
	v_fma_f32 v1, v125, v1, -v5
	v_fmac_f32_e32 v8, v1, v1
	s_nop 1
	s_waitcnt lgkmcnt(0)
	v_add_f32_dpp v5, v8, v8 quad_perm:[1,0,3,2] row_mask:0xf bank_mask:0xf
	s_nop 1
	v_add_f32_dpp v5, v5, v5 quad_perm:[2,3,0,1] row_mask:0xf bank_mask:0xf
	s_nop 1
	v_add_f32_dpp v5, v5, v5 row_half_mirror row_mask:0xf bank_mask:0xf
	s_nop 1
	v_add_f32_dpp v5, v5, v5 row_mirror row_mask:0xf bank_mask:0xf
	ds_swizzle_b32 v8, v5 offset:swizzle(SWAP,16)
	s_waitcnt lgkmcnt(0)
	v_add_f32_e32 v5, v5, v8
	v_fmamk_f32 v5, v5, 0x3c000000, v204
	v_rsq_f32_e32 v5, v5
	s_nop 0
	v_mul_f32_e32 v5, v133, v5
	v_mul_f32_e32 v0, v0, v5
	v_mul_f32_e32 v0, v132, v0
	v_mul_f32_e32 v4, v4, v5
	v_mul_f32_e32 v4, v131, v4
	v_mul_f32_e32 v8, v9, v5
	v_cvt_pk_bf16_f32 v0, v0, s0
	v_mul_f32_e32 v8, v130, v8
	v_mul_f32_e32 v1, v1, v5
	ds_write_b16 v32, v0 offset:6400
	v_cvt_pk_bf16_f32 v0, v4, s0
	v_mul_f32_e32 v1, v129, v1
	ds_write_b16 v32, v0 offset:6464
	v_cvt_pk_bf16_f32 v0, v8, s0
	ds_write_b16 v32, v0 offset:6528
	v_cvt_pk_bf16_f32 v0, v1, s0
	v_mul_f32_e32 v1, v30, v6
	ds_write_b16 v32, v0 offset:6592
	v_mul_f32_e32 v0, v14, v6
	v_fma_f32 v1, v94, v2, -v1
	v_fma_f32 v0, v78, v2, -v0
	v_mul_f32_e32 v4, v1, v1
	v_mul_f32_e32 v5, v46, v6
	v_fmac_f32_e32 v4, v0, v0
	v_fma_f32 v5, v110, v2, -v5
	v_mul_f32_e32 v6, v62, v6
	v_fmac_f32_e32 v4, v5, v5
	v_fma_f32 v2, v126, v2, -v6
	v_fmac_f32_e32 v4, v2, v2
	s_nop 1
	s_waitcnt lgkmcnt(0)
	v_add_f32_dpp v4, v4, v4 quad_perm:[1,0,3,2] row_mask:0xf bank_mask:0xf
	s_nop 1
	v_add_f32_dpp v4, v4, v4 quad_perm:[2,3,0,1] row_mask:0xf bank_mask:0xf
	s_nop 1
	v_add_f32_dpp v4, v4, v4 row_half_mirror row_mask:0xf bank_mask:0xf
	s_nop 1
	v_add_f32_dpp v4, v4, v4 row_mirror row_mask:0xf bank_mask:0xf
	ds_swizzle_b32 v6, v4 offset:swizzle(SWAP,16)
	s_waitcnt lgkmcnt(0)
	v_add_f32_e32 v4, v4, v6
	v_fmamk_f32 v4, v4, 0x3c000000, v204
	v_rsq_f32_e32 v4, v4
	s_nop 0
	v_mul_f32_e32 v4, v133, v4
	v_mul_f32_e32 v0, v0, v4
	v_mul_f32_e32 v0, v132, v0
	v_mul_f32_e32 v1, v1, v4
	v_mul_f32_e32 v1, v131, v1
	v_mul_f32_e32 v5, v5, v4
	v_cvt_pk_bf16_f32 v0, v0, s0
	v_mul_f32_e32 v5, v130, v5
	v_mul_f32_e32 v2, v2, v4
	ds_write_b16 v32, v0 offset:6656
	v_cvt_pk_bf16_f32 v0, v1, s0
	v_mul_f32_e32 v2, v129, v2
	ds_write_b16 v32, v0 offset:6720
	v_cvt_pk_bf16_f32 v0, v5, s0
	ds_write_b16 v32, v0 offset:6784
	v_cvt_pk_bf16_f32 v0, v2, s0
	v_mul_f32_e32 v1, v31, v7
	ds_write_b16 v32, v0 offset:6848
	v_mul_f32_e32 v0, v15, v7
	v_fma_f32 v1, v95, v3, -v1
	v_fma_f32 v0, v79, v3, -v0
	v_mul_f32_e32 v2, v1, v1
	v_mul_f32_e32 v4, v47, v7
	v_fmac_f32_e32 v2, v0, v0
	v_fma_f32 v4, v111, v3, -v4
	v_mul_f32_e32 v5, v63, v7
	v_fmac_f32_e32 v2, v4, v4
	v_fma_f32 v3, v127, v3, -v5
	v_fmac_f32_e32 v2, v3, v3
	s_nop 1
	s_waitcnt lgkmcnt(0)
	v_add_f32_dpp v2, v2, v2 quad_perm:[1,0,3,2] row_mask:0xf bank_mask:0xf
	s_nop 1
	v_add_f32_dpp v2, v2, v2 quad_perm:[2,3,0,1] row_mask:0xf bank_mask:0xf
	s_nop 1
	v_add_f32_dpp v2, v2, v2 row_half_mirror row_mask:0xf bank_mask:0xf
	s_nop 1
	v_add_f32_dpp v2, v2, v2 row_mirror row_mask:0xf bank_mask:0xf
	ds_swizzle_b32 v5, v2 offset:swizzle(SWAP,16)
	s_waitcnt lgkmcnt(0)
	v_add_f32_e32 v2, v2, v5
	v_fmamk_f32 v2, v2, 0x3c000000, v204
	v_rsq_f32_e32 v2, v2
	s_nop 0
	v_mul_f32_e32 v2, v133, v2
	v_mul_f32_e32 v0, v0, v2
	v_mul_f32_e32 v0, v132, v0
	v_mul_f32_e32 v1, v1, v2
	v_mul_f32_e32 v1, v131, v1
	v_mul_f32_e32 v4, v4, v2
	v_cvt_pk_bf16_f32 v0, v0, s0
	v_mul_f32_e32 v4, v130, v4
	v_mul_f32_e32 v2, v3, v2
	ds_write_b16 v32, v0 offset:6912
	v_cvt_pk_bf16_f32 v0, v1, s0
	v_mul_f32_e32 v2, v129, v2
	ds_write_b16 v32, v0 offset:6976
	v_cvt_pk_bf16_f32 v0, v4, s0
	ds_write_b16 v32, v0 offset:7040
	v_cvt_pk_bf16_f32 v0, v2, s0
	ds_write_b16 v32, v0 offset:7104
	v_lshlrev_b32_e32 v0, 4, v128
	v_and_b32_e32 v160, 0xf0, v0
	v_add_u32_e32 v6, s48, v160
	v_ashrrev_i32_e32 v4, 4, v128
	s_waitcnt lgkmcnt(0)
	v_lshl_add_u32 v0, v4, 8, v6
	ds_read_b128 v[0:3], v0
	v_ashrrev_i32_e32 v5, 31, v4
	v_lshl_add_u64 v[4:5], s[2:3], 0, v[4:5]
	v_lshlrev_b64 v[4:5], 11, v[4:5]
	v_lshl_add_u64 v[4:5], s[92:93], 0, v[4:5]
	v_lshl_add_u64 v[4:5], v[4:5], 0, v[160:161]
	s_waitcnt lgkmcnt(0)
	global_store_dwordx4 v[4:5], v[0:3], off
	s_nop 1
	v_add_u32_e32 v0, 64, v128
	v_ashrrev_i32_e32 v4, 4, v0
	v_lshl_add_u32 v0, v4, 8, v6
	ds_read_b128 v[0:3], v0
	v_ashrrev_i32_e32 v5, 31, v4
	v_lshl_add_u64 v[4:5], s[2:3], 0, v[4:5]
	v_lshlrev_b64 v[4:5], 11, v[4:5]
	v_lshl_add_u64 v[4:5], s[92:93], 0, v[4:5]
	v_lshl_add_u64 v[4:5], v[4:5], 0, v[160:161]
	s_waitcnt lgkmcnt(0)
	global_store_dwordx4 v[4:5], v[0:3], off
	s_nop 1
	v_add_u32_e32 v0, 0x80, v128
	v_ashrrev_i32_e32 v4, 4, v0
	v_lshl_add_u32 v0, v4, 8, v6
	ds_read_b128 v[0:3], v0
	v_ashrrev_i32_e32 v5, 31, v4
	v_lshl_add_u64 v[4:5], s[2:3], 0, v[4:5]
	v_lshlrev_b64 v[4:5], 11, v[4:5]
	v_lshl_add_u64 v[4:5], s[92:93], 0, v[4:5]
	v_lshl_add_u64 v[4:5], v[4:5], 0, v[160:161]
	s_waitcnt lgkmcnt(0)
	global_store_dwordx4 v[4:5], v[0:3], off
	s_nop 1
	v_add_u32_e32 v0, 0xc0, v128
	v_ashrrev_i32_e32 v4, 4, v0
	v_lshl_add_u32 v0, v4, 8, v6
	ds_read_b128 v[0:3], v0
	v_ashrrev_i32_e32 v5, 31, v4
	v_lshl_add_u64 v[4:5], s[2:3], 0, v[4:5]
	v_lshlrev_b64 v[4:5], 11, v[4:5]
	v_lshl_add_u64 v[4:5], s[92:93], 0, v[4:5]
	v_lshl_add_u64 v[4:5], v[4:5], 0, v[160:161]
	s_waitcnt lgkmcnt(0)
	global_store_dwordx4 v[4:5], v[0:3], off
	s_nop 1
	v_add_u32_e32 v0, 0x100, v128
	v_ashrrev_i32_e32 v4, 4, v0
	v_lshl_add_u32 v0, v4, 8, v6
	ds_read_b128 v[0:3], v0
	v_ashrrev_i32_e32 v5, 31, v4
	v_lshl_add_u64 v[4:5], s[2:3], 0, v[4:5]
	v_lshlrev_b64 v[4:5], 11, v[4:5]
	v_lshl_add_u64 v[4:5], s[92:93], 0, v[4:5]
	v_lshl_add_u64 v[4:5], v[4:5], 0, v[160:161]
	s_waitcnt lgkmcnt(0)
	global_store_dwordx4 v[4:5], v[0:3], off
	s_nop 1
	v_add_u32_e32 v0, 0x140, v128
	v_ashrrev_i32_e32 v4, 4, v0
	v_lshl_add_u32 v0, v4, 8, v6
	ds_read_b128 v[0:3], v0
	v_ashrrev_i32_e32 v5, 31, v4
	v_lshl_add_u64 v[4:5], s[2:3], 0, v[4:5]
	v_lshlrev_b64 v[4:5], 11, v[4:5]
	v_lshl_add_u64 v[4:5], s[92:93], 0, v[4:5]
	v_lshl_add_u64 v[4:5], v[4:5], 0, v[160:161]
	s_waitcnt lgkmcnt(0)
	global_store_dwordx4 v[4:5], v[0:3], off
	s_nop 1
	v_add_u32_e32 v0, 0x180, v128
	v_ashrrev_i32_e32 v4, 4, v0
	v_lshl_add_u32 v0, v4, 8, v6
	ds_read_b128 v[0:3], v0
	v_ashrrev_i32_e32 v5, 31, v4
	v_lshl_add_u64 v[4:5], s[2:3], 0, v[4:5]
	v_lshlrev_b64 v[4:5], 11, v[4:5]
	v_lshl_add_u64 v[4:5], s[92:93], 0, v[4:5]
	v_lshl_add_u64 v[4:5], v[4:5], 0, v[160:161]
	s_waitcnt lgkmcnt(0)
	global_store_dwordx4 v[4:5], v[0:3], off
	s_nop 1
	v_add_u32_e32 v0, 0x1c0, v128
	v_ashrrev_i32_e32 v4, 4, v0
	v_lshl_add_u32 v0, v4, 8, v6
	ds_read_b128 v[0:3], v0
	v_ashrrev_i32_e32 v5, 31, v4
	v_lshl_add_u64 v[4:5], s[2:3], 0, v[4:5]
	v_lshlrev_b64 v[4:5], 11, v[4:5]
	v_lshl_add_u64 v[4:5], s[92:93], 0, v[4:5]
	v_lshl_add_u64 v[4:5], v[4:5], 0, v[160:161]
	s_waitcnt lgkmcnt(0)
	global_store_dwordx4 v[4:5], v[0:3], off
	s_waitcnt vmcnt(0) lgkmcnt(0)
	s_barrier
	s_cbranch_scc1 .LBB0_419
